# P9a c-vector GEMM: the wave half whose rows are never stored skips its MFMA blocks; on top of the stacked version
# speedup vs baseline: 1.0076x; 1.0076x over previous
; #define PG8_STAGE(bufoff, gbase, voff) do { _Pragma("unroll") for (int _i = 0; _i < 2; ++_i) \
;         __builtin_amdgcn_global_load_lds((const unsigned*)((const char*)(gbase) + (voff)[_i]), (LAS unsigned*)(lds + (bufoff) + ldsw + _i * 8192), 16, 0, 0); } while (0)
; #define PG8_LDA(dst, b, h) do { _Pragma("unroll") for (int m = 0; m < 4; ++m) _Pragma("unroll") for (int k = 0; k < 2; ++k) dst[m][k] = *(const LAS bf16x8*)(lds + PG8_SA(b, h) + aoff + m * 2048 + k * 1024); } while (0)
; #define PG8_LDB(dst, b, h) do { _Pragma("unroll") for (int n = 0; n < 2; ++n) _Pragma("unroll") for (int k = 0; k < 2; ++k) dst[n][k] = *(const LAS bf16x8*)(lds + PG8_SB(b, h) + boff + n * 2048 + k * 1024); } while (0)
; #define PG8_WAIT_V(n) asm volatile("s_waitcnt vmcnt(" #n ")" ::: "memory")
; template <class Epi, bool ALIGN_EPI, bool SP2>
; DI void gemm_phase(int g_wave, LAS unsigned char* lds, const Gemm g, const StaticOrder& S, const Epi& E) {
;     ...
;             PG8_LDB(B0, 0, 0); PG8_LDB(B1, 0, 1); PG8_SCHED; PG8_LDA(At, 0, 0); PG8_STAGE(PG8_SA(1, 1), a1 + hstep, voffA);
;             PG8_WAIT_V(8); PG8_WAIT_L(0); PG8_BAR; PG8_MMA(0, 0, At, B0); PG8_MMA(0, 1, At, B1); PG8_BAR; PG8_SCHED;
;             PG8_LDA(At, 0, 1); PG8_STAGE(PG8_SB(0, 0), b2, voffB); PG8_STAGE(PG8_SB(0, 1), b2 + hstep, voffB); PG8_STAGE(PG8_SA(0, 0), a2, voffA);
;             PG8_WAIT_V(8); PG8_WAIT_L(0); PG8_BAR; PG8_MMA(1, 0, At, B0); PG8_MMA(1, 1, At, B1); PG8_BAR; PG8_SCHED;
;             PG8_LDB(B0, 1, 0); PG8_LDB(B1, 1, 1); PG8_SCHED; PG8_LDA(At, 1, 0); PG8_STAGE(PG8_SA(0, 1), a2 + hstep, voffA);
;             PG8_WAIT_V(8); PG8_WAIT_L(0); PG8_BAR; PG8_MMA(0, 0, At, B0); PG8_MMA(0, 1, At, B1); PG8_BAR; PG8_SCHED;
;             PG8_LDA(At, 1, 1); PG8_STAGE(PG8_SB(1, 0), b3, voffB); PG8_STAGE(PG8_SB(1, 1), b3 + hstep, voffB); PG8_STAGE(PG8_SA(1, 0), a3, voffA);
;             PG8_WAIT_V(8); PG8_WAIT_L(0); PG8_BAR; PG8_MMA(1, 0, At, B0); PG8_MMA(1, 1, At, B1); PG8_BAR; PG8_SCHED;
; __global__ void __launch_bounds__(512, 2) mega(Params P) {
;     ...
;                     EpiC ec; ec.dst = up ? WSP(float, WS_CV2) + (size_t)24 * NUP : WSP(float, WS_CV1) + (size_t)24 * NIN; ec.r0 = 32 * (2 + up); ec.ldc = up ? NUP : NIN;
;                     run_gemm_w(g_wave, lds, WSP(bf16_t, WS_SHM), (const bf16_t*)(ws + WS_W + W_LAYER + (up ? W_UP : W_IN)), 256, up ? NUP : NIN, 1024, G - (up ? 26 : 16), ec);
.LBB0_1638:
	s_add_u32 s34, s12, 0xfffc0080
	s_addc_u32 s35, s13, -1
	s_add_i32 s72, 0, 0x10000
	s_cmp_eq_u32 s71, 12
	s_cselect_b32 s37, s17, s35
	s_cselect_b32 s36, s27, s34
	v_add_u32_e32 v140, s72, v142
	s_cselect_b32 s35, s25, s70
	s_cselect_b32 s34, s66, s67
	s_add_i32 s74, 0, 0x14000
	ds_read_b128 v[144:147], v140
	ds_read_b128 v[148:151], v140 offset:1024
	ds_read_b128 v[152:155], v140 offset:2048
	ds_read_b128 v[156:159], v140 offset:3072
	v_add_u32_e32 v140, s74, v142
	ds_read_b128 v[160:163], v140
	ds_read_b128 v[164:167], v140 offset:1024
	ds_read_b128 v[168:171], v140 offset:2048
	ds_read_b128 v[172:175], v140 offset:3072
	v_lshl_add_u64 v[140:141], s[12:13], 0, v[136:137]
	s_add_i32 m0, s47, 0xc000
	ds_read_b128 v[176:179], v143
	ds_read_b128 v[180:183], v143 offset:1024
	ds_read_b128 v[184:187], v143 offset:2048
	ds_read_b128 v[188:191], v143 offset:3072
	ds_read_b128 v[192:195], v143 offset:4096
	ds_read_b128 v[196:199], v143 offset:5120
	ds_read_b128 v[200:203], v143 offset:6144
	ds_read_b128 v[204:207], v143 offset:7168
	global_load_lds_dwordx4 v[140:141], off
	v_lshl_add_u64 v[140:141], s[12:13], 0, v[138:139]
	s_add_i32 m0, s47, 0xe000
	s_nop 0
	global_load_lds_dwordx4 v[140:141], off
	s_waitcnt vmcnt(8)
	s_waitcnt lgkmcnt(0)
	s_barrier
	s_setprio 1
	s_waitcnt lgkmcnt(0)
	s_cmp_lt_u32 s21, 4
	s_cbranch_scc1 .Lcvsk_0
	v_mfma_f32_16x16x32_bf16 v[124:127], v[144:147], v[176:179], v[124:127]
	v_mfma_f32_16x16x32_bf16 v[120:123], v[152:155], v[176:179], v[120:123]
	v_mfma_f32_16x16x32_bf16 v[116:119], v[144:147], v[184:187], v[116:119]
	v_mfma_f32_16x16x32_bf16 v[108:111], v[152:155], v[184:187], v[108:111]
	v_mfma_f32_16x16x32_bf16 v[100:103], v[144:147], v[192:195], v[100:103]
	v_mfma_f32_16x16x32_bf16 v[96:99], v[152:155], v[192:195], v[96:99]
	v_mfma_f32_16x16x32_bf16 v[84:87], v[144:147], v[200:203], v[84:87]
	v_mfma_f32_16x16x32_bf16 v[80:83], v[152:155], v[200:203], v[80:83]
	v_mfma_f32_16x16x32_bf16 v[124:127], v[148:151], v[180:183], v[124:127]
	v_mfma_f32_16x16x32_bf16 v[120:123], v[156:159], v[180:183], v[120:123]
	v_mfma_f32_16x16x32_bf16 v[116:119], v[148:151], v[188:191], v[116:119]
	v_mfma_f32_16x16x32_bf16 v[108:111], v[156:159], v[188:191], v[108:111]
	v_mfma_f32_16x16x32_bf16 v[100:103], v[148:151], v[196:199], v[100:103]
	v_mfma_f32_16x16x32_bf16 v[96:99], v[156:159], v[196:199], v[96:99]
	v_mfma_f32_16x16x32_bf16 v[84:87], v[148:151], v[204:207], v[84:87]
	v_mfma_f32_16x16x32_bf16 v[80:83], v[156:159], v[204:207], v[80:83]
.Lcvsk_0:
	s_setprio 0
	s_setprio 1
	s_cmp_lt_u32 s21, 4
	s_cbranch_scc1 .Lcvsk_1
	v_mfma_f32_16x16x32_bf16 v[112:115], v[160:163], v[176:179], v[112:115]
	v_mfma_f32_16x16x32_bf16 v[104:107], v[168:171], v[176:179], v[104:107]
	v_mfma_f32_16x16x32_bf16 v[92:95], v[160:163], v[184:187], v[92:95]
	v_mfma_f32_16x16x32_bf16 v[88:91], v[168:171], v[184:187], v[88:91]
	v_mfma_f32_16x16x32_bf16 v[76:79], v[160:163], v[192:195], v[76:79]
	v_mfma_f32_16x16x32_bf16 v[72:75], v[168:171], v[192:195], v[72:75]
	v_mfma_f32_16x16x32_bf16 v[68:71], v[160:163], v[200:203], v[68:71]
	v_mfma_f32_16x16x32_bf16 v[64:67], v[168:171], v[200:203], v[64:67]
	v_mfma_f32_16x16x32_bf16 v[112:115], v[164:167], v[180:183], v[112:115]
	v_mfma_f32_16x16x32_bf16 v[104:107], v[172:175], v[180:183], v[104:107]
	v_mfma_f32_16x16x32_bf16 v[92:95], v[164:167], v[188:191], v[92:95]
	v_mfma_f32_16x16x32_bf16 v[88:91], v[172:175], v[188:191], v[88:91]
	v_mfma_f32_16x16x32_bf16 v[76:79], v[164:167], v[196:199], v[76:79]
	v_mfma_f32_16x16x32_bf16 v[72:75], v[172:175], v[196:199], v[72:75]
	v_mfma_f32_16x16x32_bf16 v[68:71], v[164:167], v[204:207], v[68:71]
	v_mfma_f32_16x16x32_bf16 v[64:67], v[172:175], v[204:207], v[64:67]
.Lcvsk_1:
	s_setprio 0
	s_barrier
	s_add_i32 s72, s72, s46
	v_lshl_add_u64 v[140:141], s[34:35], 0, v[130:131]
	s_mov_b32 m0, s72
	global_load_lds_dwordx4 v[140:141], off
	s_add_i32 m0, s72, 0x2000
	s_add_u32 s72, s34, 0x40000
	v_lshl_add_u64 v[208:209], s[34:35], 0, v[134:135]
	s_addc_u32 s73, s35, 0
	s_add_i32 s74, s74, s46
	global_load_lds_dwordx4 v[208:209], off
	v_lshl_add_u64 v[210:211], s[72:73], 0, v[130:131]
	s_mov_b32 m0, s74
	v_lshl_add_u64 v[212:213], s[36:37], 0, v[132:133]
	global_load_lds_dwordx4 v[210:211], off
	v_lshl_add_u64 v[210:211], s[72:73], 0, v[134:135]
	s_add_i32 m0, s74, 0x2000
	s_nop 0
	global_load_lds_dwordx4 v[210:211], off
	v_lshl_add_u64 v[210:211], s[36:37], 0, v[128:129]
	s_mov_b32 m0, s47
	s_nop 0
	global_load_lds_dwordx4 v[210:211], off
	s_mov_b32 m0, s49
	s_nop 0
	global_load_lds_dwordx4 v[212:213], off
	s_waitcnt vmcnt(8)
	s_waitcnt lgkmcnt(0)
	s_barrier
	s_setprio 1
	s_waitcnt lgkmcnt(0)
	s_setprio 0
	s_setprio 1
	s_setprio 0
	s_barrier
	s_add_i32 s72, 0, 0x18000
	s_add_i32 s73, 0, 0x1c000
	v_add_u32_e32 v156, s72, v142
	v_add_u32_e32 v172, s73, v142
	ds_read_b128 v[144:147], v156
	ds_read_b128 v[148:151], v156 offset:1024
	ds_read_b128 v[152:155], v156 offset:2048
	ds_read_b128 v[156:159], v156 offset:3072
	ds_read_b128 v[160:163], v172
	ds_read_b128 v[164:167], v172 offset:1024
	ds_read_b128 v[168:171], v172 offset:2048
	ds_read_b128 v[172:175], v172 offset:3072
	s_add_u32 s36, s36, 0x40000
	s_addc_u32 s37, s37, 0
	s_mov_b32 m0, s52
	v_lshl_add_u64 v[214:215], s[36:37], 0, v[128:129]
	ds_read_b128 v[176:179], v143 offset:32768
	ds_read_b128 v[180:183], v143 offset:33792
	ds_read_b128 v[184:187], v143 offset:34816
	ds_read_b128 v[188:191], v143 offset:35840
	ds_read_b128 v[192:195], v143 offset:36864
	ds_read_b128 v[196:199], v143 offset:37888
	ds_read_b128 v[200:203], v143 offset:38912
	ds_read_b128 v[204:207], v143 offset:39936
	global_load_lds_dwordx4 v[214:215], off
	v_lshl_add_u64 v[214:215], s[36:37], 0, v[132:133]
	s_mov_b32 m0, s53
	s_nop 0
	global_load_lds_dwordx4 v[214:215], off
	s_waitcnt vmcnt(8)
	s_waitcnt lgkmcnt(0)
	s_barrier
	s_setprio 1
	s_waitcnt lgkmcnt(0)
	s_cmp_lt_u32 s21, 4
	s_cbranch_scc1 .Lcvsk_4
	v_mfma_f32_16x16x32_bf16 v[124:127], v[144:147], v[176:179], v[124:127]
	v_mfma_f32_16x16x32_bf16 v[120:123], v[152:155], v[176:179], v[120:123]
	v_mfma_f32_16x16x32_bf16 v[116:119], v[144:147], v[184:187], v[116:119]
	v_mfma_f32_16x16x32_bf16 v[108:111], v[152:155], v[184:187], v[108:111]
	v_mfma_f32_16x16x32_bf16 v[100:103], v[144:147], v[192:195], v[100:103]
	v_mfma_f32_16x16x32_bf16 v[96:99], v[152:155], v[192:195], v[96:99]
	v_mfma_f32_16x16x32_bf16 v[84:87], v[144:147], v[200:203], v[84:87]
	v_mfma_f32_16x16x32_bf16 v[80:83], v[152:155], v[200:203], v[80:83]
	v_mfma_f32_16x16x32_bf16 v[124:127], v[148:151], v[180:183], v[124:127]
	v_mfma_f32_16x16x32_bf16 v[120:123], v[156:159], v[180:183], v[120:123]
	v_mfma_f32_16x16x32_bf16 v[116:119], v[148:151], v[188:191], v[116:119]
	v_mfma_f32_16x16x32_bf16 v[108:111], v[156:159], v[188:191], v[108:111]
	v_mfma_f32_16x16x32_bf16 v[100:103], v[148:151], v[196:199], v[100:103]
	v_mfma_f32_16x16x32_bf16 v[96:99], v[156:159], v[196:199], v[96:99]
	v_mfma_f32_16x16x32_bf16 v[84:87], v[148:151], v[204:207], v[84:87]
	v_mfma_f32_16x16x32_bf16 v[80:83], v[156:159], v[204:207], v[80:83]

; #define PG8_STAGE(bufoff, gbase, voff) do { _Pragma("unroll") for (int _i = 0; _i < 2; ++_i) \
;         __builtin_amdgcn_global_load_lds((const unsigned*)((const char*)(gbase) + (voff)[_i]), (LAS unsigned*)(lds + (bufoff) + ldsw + _i * 8192), 16, 0, 0); } while (0)
; #define PG8_LDA(dst, b, h) do { _Pragma("unroll") for (int m = 0; m < 4; ++m) _Pragma("unroll") for (int k = 0; k < 2; ++k) dst[m][k] = *(const LAS bf16x8*)(lds + PG8_SA(b, h) + aoff + m * 2048 + k * 1024); } while (0)
; #define PG8_MMA(ai, bj, At, Bt) do { __builtin_amdgcn_s_setprio(1); _Pragma("unroll") for (int m = 0; m < 4; ++m) _Pragma("unroll") for (int n = 0; n < 2; ++n) _Pragma("unroll") for (int k = 0; k < 2; ++k) \
;         acc[ai][bj][m][n] = __builtin_amdgcn_mfma_f32_16x16x32_bf16(Bt[n][k], At[m][k], acc[ai][bj][m][n], 0, 0, 0); __builtin_amdgcn_s_setprio(0); } while (0)
; #define PG8_WAIT_V(n) asm volatile("s_waitcnt vmcnt(" #n ")" ::: "memory")
; #define PG8_WAIT_L(n) asm volatile("s_waitcnt lgkmcnt(" #n ")" ::: "memory")
; #define PG8_BAR __builtin_amdgcn_s_barrier()
; #define PG8_SCHED __builtin_amdgcn_sched_barrier(0)
; template <class Epi, bool ALIGN_EPI, bool SP2>
; DI void gemm_phase(int g_wave, LAS unsigned char* lds, const Gemm g, const StaticOrder& S, const Epi& E) {
;     ...
;             PG8_LDA(At, 1, 1); PG8_STAGE(PG8_SB(1, 0), b3, voffB); PG8_STAGE(PG8_SB(1, 1), b3 + hstep, voffB); PG8_STAGE(PG8_SA(1, 0), a3, voffA);
;             PG8_WAIT_V(8); PG8_WAIT_L(0); PG8_BAR; PG8_MMA(1, 0, At, B0); PG8_MMA(1, 1, At, B1); PG8_BAR; PG8_SCHED;
.Lcvsk_5:
	s_setprio 0
	s_barrier
	s_add_i32 s36, s72, s46
	v_lshl_add_u64 v[140:141], v[140:141], 0, s[68:69]
	s_mov_b32 m0, s36
	global_load_lds_dwordx4 v[140:141], off
	s_add_i32 m0, s36, 0x2000
	s_add_u32 s34, s34, 0x40080
	v_lshl_add_u64 v[140:141], v[208:209], 0, s[68:69]
	s_addc_u32 s35, s35, 0
	s_add_i32 s36, s73, s46
	global_load_lds_dwordx4 v[140:141], off
	v_lshl_add_u64 v[140:141], s[34:35], 0, v[130:131]
	s_mov_b32 m0, s36
	s_nop 0
	global_load_lds_dwordx4 v[140:141], off
	v_lshl_add_u64 v[140:141], s[34:35], 0, v[134:135]
	s_add_i32 m0, s36, 0x2000
	s_nop 0
	global_load_lds_dwordx4 v[140:141], off
	v_lshl_add_u64 v[140:141], v[210:211], 0, s[68:69]
	s_mov_b32 m0, s56
	s_nop 0
	global_load_lds_dwordx4 v[140:141], off
	v_lshl_add_u64 v[140:141], v[212:213], 0, s[68:69]
	s_mov_b32 m0, s57
	s_nop 0
	global_load_lds_dwordx4 v[140:141], off
	s_waitcnt vmcnt(8)
	s_waitcnt lgkmcnt(0)
	s_barrier
	s_setprio 1
	s_waitcnt lgkmcnt(0)
	s_setprio 0
	s_setprio 1
	s_setprio 0
	s_barrier
	s_add_i32 s71, s71, 2
	s_add_u32 s12, s12, 0x100
	s_addc_u32 s13, s13, 0
	s_add_u32 s67, s67, 0x100
	s_addc_u32 s70, s70, 0
	s_cmp_gt_u32 s71, 13
	s_cbranch_scc0 .LBB0_1638
	s_and_b64 vcc, exec, s[18:19]
	s_cbranch_vccz .LBB0_1641
	s_barrier
